# out-proj 256x128 K loop unrolled by the 3 ring slots: static slot addresses and DMA targets, per-block address adds and slot bookkeeping removed
# baseline (speedup 1.0000x reference)
; DI int otid() { int t = threadIdx.x; asm volatile("" : "+v"(t)); return t; }
; #define G_ISSUE(ks_, buf_) do { \
;     const bf16_t* wq_ = wp + (ks_) * wks; const bf16_t* xq_ = xp + (ks_) * xks; char* lb_ = ld + (buf_) * STAGE; \
;     dma16(wq_, lb_); dma16(wq_ + 2048, lb_ + 4096); \
;     _Pragma("unroll") for (int i_ = 0; i_ < TJ; ++i_) dma16(xq_ + i_ * 2048, lb_ + 8192 + i_ * 4096); } while (0)
; template <bool VMODE, int TJ>
; DI void gemm_mainloop(const bf16_t* __restrict__ W, const bf16_t* __restrict__ X, int NW, char* smem, f32x16 (&acc)[2][TJ]) {
;     ...
;         G_ISSUE(0, 0);
;         G_ISSUE(1, 1);
;         int bc = 0, bn = 2;
;         for (int ks = 0; ks < 32; ++ks) {
;             if (ks < 31) asm volatile("s_waitcnt vmcnt(6)" ::: "memory");
;             else asm volatile("s_waitcnt vmcnt(0)" ::: "memory");
;             __builtin_amdgcn_s_barrier();
; template <int TJ>
; DI void outproj_tile(const Params& p, int l, char* smem, int b, int trow0, int n0) {
;     const int tid = otid(), lane = tid & 63, wave = tid >> 6, r = lane & 31, h = lane >> 5, wf = wave & 1, wt = wave >> 1;
;     const bf16_t* W = p.wtout + (size_t)l * D * D + (size_t)n0 * 32;
;     const bf16_t* X = p.hmix + ((size_t)b * TPB + trow0) * 32;
;     f32x16 acc[2][TJ];
;     zero_acc<TJ>(acc);
;     gemm_mainloop<false, TJ>(W, X, D, smem, acc);
.LBB0_39:
	v_mov_b32_e32 v116, v200
	s_cmp_lg_u32 s6, 0
	s_cbranch_scc1 .Lop4_second
	s_load_dwordx2 s[8:9], s[0:1], 0xd8
	s_load_dwordx2 s[56:57], s[0:1], 0xb8
	s_mov_b64 s[62:63], 0
	v_readlane_b32 s4, v254, 13
	s_nop 0
	s_add_i32 s4, s6, s4
	s_and_b32 s28, s4, 0x7fffff80
	s_waitcnt lgkmcnt(0)
	s_add_u32 s8, s8, s58
	s_addc_u32 s9, s9, s59
	v_readlane_b32 s4, v254, 14
	s_nop 0
	s_add_u32 s4, s8, s4
	s_addc_u32 s5, s9, 0
	v_readlane_b32 s6, v255, 23
	s_nop 0
	s_add_i32 s6, s6, s28
	s_mov_b32 s7, s75
	s_lshl_b64 s[6:7], s[6:7], 6
	s_add_u32 s6, s56, s6
	s_addc_u32 s7, s57, s7
	v_bfe_u32 v1, v200, 4, 2
	v_bitop3_b32 v1, v1, v200, 3 bitop3:0x78
	v_lshlrev_b32_e32 v0, 3, v200
	v_lshlrev_b32_e32 v1, 3, v1
	s_movk_i32 s29, 0xffe0
	v_and_or_b32 v0, v0, s29, v1
	v_lshlrev_b32_e32 v128, 1, v0
	v_lshl_add_u32 v130, v200, 4, 32
	v_bfe_u32 v5, v200, 5, 1
	v_bfe_u32 v7, v200, 2, 2
	v_bitop3_b32 v9, v5, v7, 2 bitop3:0x36
	v_lshrrev_b32_e32 v6, 2, v200
	v_lshlrev_b32_e32 v8, 6, v200
	v_bitop3_b32 v6, v5, v6, 3 bitop3:0x78
	v_and_b32_e32 v10, 0x7c0, v8
	v_lshl_or_b32 v131, v6, 4, v10
	v_lshl_or_b32 v132, v9, 4, v10
	v_and_b32_e32 v134, 0x1000, v8
	v_and_b32_e32 v133, 0xffffe000, v8
	v_mov_b32_e32 v170, v128
	v_add_u32_e32 v171, 0x1000, v128
	v_add_u32_e32 v172, 0x10000, v128
	v_add_u32_e32 v173, 0x11000, v128
	v_readfirstlane_b32 s100, v130
	v_mov_b32_e32 v0, 0
	v_mov_b32_e32 v1, 0
	v_mov_b32_e32 v2, 0
	v_mov_b32_e32 v3, 0
	v_mov_b32_e32 v4, 0
	v_mov_b32_e32 v5, 0
	v_mov_b32_e32 v6, 0
	v_mov_b32_e32 v7, 0
	v_mov_b32_e32 v8, 0
	v_mov_b32_e32 v9, 0
	v_mov_b32_e32 v10, 0
	v_mov_b32_e32 v11, 0
	v_mov_b32_e32 v12, 0
	v_mov_b32_e32 v13, 0
	v_mov_b32_e32 v14, 0
	v_mov_b32_e32 v15, 0
	v_mov_b32_e32 v16, 0
	v_mov_b32_e32 v17, 0
	v_mov_b32_e32 v18, 0
	v_mov_b32_e32 v19, 0
	v_mov_b32_e32 v20, 0
	v_mov_b32_e32 v21, 0
	v_mov_b32_e32 v22, 0
	v_mov_b32_e32 v23, 0
	v_mov_b32_e32 v24, 0
	v_mov_b32_e32 v25, 0
	v_mov_b32_e32 v26, 0
	v_mov_b32_e32 v27, 0
	v_mov_b32_e32 v28, 0
	v_mov_b32_e32 v29, 0
	v_mov_b32_e32 v30, 0
	v_mov_b32_e32 v31, 0
	v_mov_b32_e32 v32, 0
	v_mov_b32_e32 v33, 0
	v_mov_b32_e32 v34, 0
	v_mov_b32_e32 v35, 0
	v_mov_b32_e32 v36, 0
	v_mov_b32_e32 v37, 0
	v_mov_b32_e32 v38, 0
	v_mov_b32_e32 v39, 0
	v_mov_b32_e32 v40, 0
	v_mov_b32_e32 v41, 0
	v_mov_b32_e32 v42, 0
	v_mov_b32_e32 v43, 0
	v_mov_b32_e32 v44, 0
	v_mov_b32_e32 v45, 0
	v_mov_b32_e32 v46, 0
	v_mov_b32_e32 v47, 0
	v_mov_b32_e32 v48, 0
	v_mov_b32_e32 v49, 0
	v_mov_b32_e32 v50, 0
	v_mov_b32_e32 v51, 0
	v_mov_b32_e32 v52, 0
	v_mov_b32_e32 v53, 0
	v_mov_b32_e32 v54, 0
	v_mov_b32_e32 v55, 0
	v_mov_b32_e32 v56, 0
	v_mov_b32_e32 v57, 0
	v_mov_b32_e32 v58, 0
	v_mov_b32_e32 v59, 0
	v_mov_b32_e32 v60, 0
	v_mov_b32_e32 v61, 0
	v_mov_b32_e32 v62, 0
	v_mov_b32_e32 v63, 0
	v_mov_b32_e32 v64, 0
	v_mov_b32_e32 v65, 0
	v_mov_b32_e32 v66, 0
	v_mov_b32_e32 v67, 0
	v_mov_b32_e32 v68, 0
	v_mov_b32_e32 v69, 0
	v_mov_b32_e32 v70, 0
	v_mov_b32_e32 v71, 0
	v_mov_b32_e32 v72, 0
	v_mov_b32_e32 v73, 0
	v_mov_b32_e32 v74, 0
	v_mov_b32_e32 v75, 0
	v_mov_b32_e32 v76, 0
	v_mov_b32_e32 v77, 0
	v_mov_b32_e32 v78, 0
	v_mov_b32_e32 v79, 0
	v_mov_b32_e32 v80, 0
	v_mov_b32_e32 v81, 0
	v_mov_b32_e32 v82, 0
	v_mov_b32_e32 v83, 0
	v_mov_b32_e32 v84, 0
	v_mov_b32_e32 v85, 0
	v_mov_b32_e32 v86, 0
	v_mov_b32_e32 v87, 0
	v_mov_b32_e32 v88, 0
	v_mov_b32_e32 v89, 0
	v_mov_b32_e32 v90, 0
	v_mov_b32_e32 v91, 0
	v_mov_b32_e32 v92, 0
	v_mov_b32_e32 v93, 0
	v_mov_b32_e32 v94, 0
	v_mov_b32_e32 v95, 0
	v_mov_b32_e32 v96, 0
	v_mov_b32_e32 v97, 0
	v_mov_b32_e32 v98, 0
	v_mov_b32_e32 v99, 0
	v_mov_b32_e32 v100, 0
	v_mov_b32_e32 v101, 0
	v_mov_b32_e32 v102, 0
	v_mov_b32_e32 v103, 0
	v_mov_b32_e32 v104, 0
	v_mov_b32_e32 v105, 0
	v_mov_b32_e32 v106, 0
	v_mov_b32_e32 v107, 0
	v_mov_b32_e32 v108, 0
	v_mov_b32_e32 v109, 0
	v_mov_b32_e32 v110, 0
	v_mov_b32_e32 v111, 0
	v_mov_b32_e32 v112, 0
	v_mov_b32_e32 v113, 0
	v_mov_b32_e32 v114, 0
	v_mov_b32_e32 v115, 0
	v_mov_b32_e32 v116, 0
	v_mov_b32_e32 v117, 0
	v_mov_b32_e32 v118, 0
	v_mov_b32_e32 v119, 0
	v_mov_b32_e32 v120, 0
	v_mov_b32_e32 v121, 0
	v_mov_b32_e32 v122, 0
	v_mov_b32_e32 v123, 0
	v_mov_b32_e32 v124, 0
	v_mov_b32_e32 v125, 0
	v_mov_b32_e32 v126, 0
	v_mov_b32_e32 v127, 0
	s_barrier
	s_mov_b32 s101, s100
	s_mov_b32 m0, s101
	s_nop 0
	global_load_lds_dwordx4 v170, s[4:5]
	s_add_u32 m0, s101, 0x1000
	s_nop 0
	global_load_lds_dwordx4 v171, s[4:5]
	s_add_u32 m0, s101, 0x2000
	s_nop 0
	global_load_lds_dwordx4 v172, s[6:7]
	s_add_u32 m0, s101, 0x3000
	s_nop 0
	global_load_lds_dwordx4 v170, s[6:7]
	s_add_u32 m0, s101, 0x4000
	s_nop 0
	global_load_lds_dwordx4 v173, s[6:7]
	s_add_u32 m0, s101, 0x5000
	s_nop 0
	global_load_lds_dwordx4 v171, s[6:7]
	s_add_u32 s4, s4, 0x10000
	s_addc_u32 s5, s5, 0
	s_add_u32 s6, s6, 0x120000
	s_addc_u32 s7, s7, 0
	s_add_i32 s101, s100, 0x6000
	s_mov_b32 m0, s101
	s_nop 0
	global_load_lds_dwordx4 v170, s[4:5]
	s_add_u32 m0, s101, 0x1000
	s_nop 0
	global_load_lds_dwordx4 v171, s[4:5]
	s_add_u32 m0, s101, 0x2000
	s_nop 0
	global_load_lds_dwordx4 v172, s[6:7]
	s_add_u32 m0, s101, 0x3000
	s_nop 0
	global_load_lds_dwordx4 v170, s[6:7]
	s_add_u32 m0, s101, 0x4000
	s_nop 0
	global_load_lds_dwordx4 v173, s[6:7]
	s_add_u32 m0, s101, 0x5000
	s_nop 0
	global_load_lds_dwordx4 v171, s[6:7]
	s_add_u32 s4, s4, 0x10000
	s_addc_u32 s5, s5, 0
	s_add_u32 s6, s6, 0x120000
	s_addc_u32 s7, s7, 0
	s_mov_b32 s29, 29
	v_add_u32_e32 v214, v134, v131
	v_add_u32_e32 v215, v133, v131
	v_add_u32_e32 v216, v134, v132
	v_add_u32_e32 v217, v133, v132
	v_add_u32_e32 v214, 0x20, v214
	v_add_u32_e32 v215, 0x20, v215
	v_add_u32_e32 v216, 0x20, v216
	v_add_u32_e32 v217, 0x20, v217
	v_add_u32_e32 v218, v134, v131
	v_add_u32_e32 v219, v133, v131
	v_add_u32_e32 v220, v134, v132
	v_add_u32_e32 v221, v133, v132
	v_add_u32_e32 v218, 0x6020, v218
	v_add_u32_e32 v219, 0x6020, v219
	v_add_u32_e32 v220, 0x6020, v220
	v_add_u32_e32 v221, 0x6020, v221
	v_add_u32_e32 v222, v134, v131
	v_add_u32_e32 v223, v133, v131
	v_add_u32_e32 v224, v134, v132
	v_add_u32_e32 v225, v133, v132
	v_add_u32_e32 v222, 0xc020, v222
	v_add_u32_e32 v223, 0xc020, v223
	v_add_u32_e32 v224, 0xc020, v224
	v_add_u32_e32 v225, 0xc020, v225
	s_waitcnt vmcnt(6)
	s_waitcnt lgkmcnt(0)
	s_barrier
; #define MFMA(a, b, c) __builtin_amdgcn_mfma_f32_32x32x16_bf16((a), (b), (c), 0, 0, 0)
; #define G_ISSUE(ks_, buf_) do { \
;     const bf16_t* wq_ = wp + (ks_) * wks; const bf16_t* xq_ = xp + (ks_) * xks; char* lb_ = ld + (buf_) * STAGE; \
;     dma16(wq_, lb_); dma16(wq_ + 2048, lb_ + 4096); \
;     _Pragma("unroll") for (int i_ = 0; i_ < TJ; ++i_) dma16(xq_ + i_ * 2048, lb_ + 8192 + i_ * 4096); } while (0)
; template <bool VMODE, int TJ>
; DI void gemm_mainloop(const bf16_t* __restrict__ W, const bf16_t* __restrict__ X, int NW, char* smem, f32x16 (&acc)[2][TJ]) {
;     ...
;         for (int ks = 0; ks < 32; ++ks) {
;             if (ks < 31) asm volatile("s_waitcnt vmcnt(6)" ::: "memory");
;             else asm volatile("s_waitcnt vmcnt(0)" ::: "memory");
;             __builtin_amdgcn_s_barrier();
;             const char* sw = smem + bc * STAGE + wf * 64 * 64;
;             const char* sx = smem + bc * STAGE + 8192 + wt * (32 * TJ) * 64;
;             bf16x8 fw[2], fx[TJ], gw[2], gx[TJ];
; #pragma unroll
;             for (int i = 0; i < 2; ++i) fw[i] = *(const bf16x8*)(sw + i * 32 * 64 + fo0);
; #pragma unroll
;             for (int j = 0; j < TJ; ++j) fx[j] = *(const bf16x8*)(sx + j * 32 * 64 + fo0);
;             __builtin_amdgcn_sched_barrier(0);
;             if (ks + 2 < 32) G_ISSUE(ks + 2, bn);
;             __builtin_amdgcn_sched_barrier(0);
; #pragma unroll
;             for (int i = 0; i < 2; ++i) gw[i] = *(const bf16x8*)(sw + i * 32 * 64 + fo1);
; #pragma unroll
;             for (int j = 0; j < TJ; ++j) gx[j] = *(const bf16x8*)(sx + j * 32 * 64 + fo1);
; #pragma unroll
;             for (int i = 0; i < 2; ++i)
; #pragma unroll
;                 for (int j = 0; j < TJ; ++j) acc[i][j] = VMODE ? MFMA(fx[j], fw[i], acc[i][j]) : MFMA(fw[i], fx[j], acc[i][j]);
; #pragma unroll
;             for (int i = 0; i < 2; ++i)
; #pragma unroll
;                 for (int j = 0; j < TJ; ++j) acc[i][j] = VMODE ? MFMA(gx[j], gw[i], acc[i][j]) : MFMA(gw[i], gx[j], acc[i][j]);
	ds_read_b128 v[136:139], v214
	ds_read_b128 v[140:143], v214 offset:2048
	ds_read_b128 v[144:147], v215 offset:8192
	ds_read_b128 v[148:151], v215 offset:10240
	ds_read_b128 v[152:155], v215 offset:12288
	ds_read_b128 v[156:159], v215 offset:14336
	s_add_i32 s101, s100, 0xc000
	s_mov_b32 m0, s101
	s_nop 0
	global_load_lds_dwordx4 v170, s[4:5]
	s_add_u32 m0, s101, 0x1000
	s_nop 0
	global_load_lds_dwordx4 v171, s[4:5]
	s_add_u32 m0, s101, 0x2000
	s_nop 0
	global_load_lds_dwordx4 v172, s[6:7]
	s_add_u32 m0, s101, 0x3000
	s_nop 0
	global_load_lds_dwordx4 v170, s[6:7]
	s_add_u32 m0, s101, 0x4000
	s_nop 0
	global_load_lds_dwordx4 v173, s[6:7]
	s_add_u32 m0, s101, 0x5000
	s_nop 0
	global_load_lds_dwordx4 v171, s[6:7]
	s_add_u32 s4, s4, 0x10000
	s_addc_u32 s5, s5, 0
	s_add_u32 s6, s6, 0x120000
	s_addc_u32 s7, s7, 0
	s_waitcnt lgkmcnt(0)
	v_mfma_f32_32x32x16_bf16 v[112:127], v[136:139], v[144:147], v[112:127]
	ds_read_b128 v[160:163], v216
	v_mfma_f32_32x32x16_bf16 v[96:111], v[136:139], v[148:151], v[96:111]
	ds_read_b128 v[176:179], v216 offset:2048
	v_mfma_f32_32x32x16_bf16 v[48:63], v[136:139], v[152:155], v[48:63]
	ds_read_b128 v[164:167], v217 offset:8192
	v_mfma_f32_32x32x16_bf16 v[32:47], v[136:139], v[156:159], v[32:47]
	ds_read_b128 v[180:183], v217 offset:10240
	v_mfma_f32_32x32x16_bf16 v[80:95], v[140:143], v[144:147], v[80:95]
	ds_read_b128 v[184:187], v217 offset:12288
	v_mfma_f32_32x32x16_bf16 v[64:79], v[140:143], v[148:151], v[64:79]
	ds_read_b128 v[188:191], v217 offset:14336
	v_mfma_f32_32x32x16_bf16 v[16:31], v[140:143], v[152:155], v[16:31]
	v_mfma_f32_32x32x16_bf16 v[0:15], v[140:143], v[156:159], v[0:15]
.Lop4_loop:
	s_waitcnt vmcnt(6)
	s_waitcnt lgkmcnt(0)
	s_barrier
	ds_read_b128 v[136:139], v218
	ds_read_b128 v[140:143], v218 offset:2048
	ds_read_b128 v[144:147], v219 offset:8192
	ds_read_b128 v[148:151], v219 offset:10240
	ds_read_b128 v[152:155], v219 offset:12288
	ds_read_b128 v[156:159], v219 offset:14336
	s_add_i32 s101, s100, 0x0
	s_mov_b32 m0, s101
	v_mfma_f32_32x32x16_bf16 v[112:127], v[160:163], v[164:167], v[112:127]
	global_load_lds_dwordx4 v170, s[4:5]
	s_add_u32 m0, s101, 0x1000
	v_mfma_f32_32x32x16_bf16 v[96:111], v[160:163], v[180:183], v[96:111]
	global_load_lds_dwordx4 v171, s[4:5]
	s_add_u32 m0, s101, 0x2000
	v_mfma_f32_32x32x16_bf16 v[48:63], v[160:163], v[184:187], v[48:63]
	global_load_lds_dwordx4 v172, s[6:7]
	s_add_u32 m0, s101, 0x3000
	v_mfma_f32_32x32x16_bf16 v[32:47], v[160:163], v[188:191], v[32:47]
	global_load_lds_dwordx4 v170, s[6:7]
	s_add_u32 m0, s101, 0x4000
	v_mfma_f32_32x32x16_bf16 v[80:95], v[176:179], v[164:167], v[80:95]
	global_load_lds_dwordx4 v173, s[6:7]
	s_add_u32 m0, s101, 0x5000
	v_mfma_f32_32x32x16_bf16 v[64:79], v[176:179], v[180:183], v[64:79]
	global_load_lds_dwordx4 v171, s[6:7]
	s_add_u32 s4, s4, 0x10000
	s_addc_u32 s5, s5, 0
	s_add_u32 s6, s6, 0x120000
	s_addc_u32 s7, s7, 0
	v_mfma_f32_32x32x16_bf16 v[16:31], v[176:179], v[184:187], v[16:31]
	v_mfma_f32_32x32x16_bf16 v[0:15], v[176:179], v[188:191], v[0:15]
	s_waitcnt lgkmcnt(0)
	v_mfma_f32_32x32x16_bf16 v[112:127], v[136:139], v[144:147], v[112:127]
	ds_read_b128 v[160:163], v220
	v_mfma_f32_32x32x16_bf16 v[96:111], v[136:139], v[148:151], v[96:111]
	ds_read_b128 v[176:179], v220 offset:2048
	v_mfma_f32_32x32x16_bf16 v[48:63], v[136:139], v[152:155], v[48:63]
	ds_read_b128 v[164:167], v221 offset:8192
	v_mfma_f32_32x32x16_bf16 v[32:47], v[136:139], v[156:159], v[32:47]
	ds_read_b128 v[180:183], v221 offset:10240
	v_mfma_f32_32x32x16_bf16 v[80:95], v[140:143], v[144:147], v[80:95]
	ds_read_b128 v[184:187], v221 offset:12288
	v_mfma_f32_32x32x16_bf16 v[64:79], v[140:143], v[148:151], v[64:79]
	ds_read_b128 v[188:191], v221 offset:14336
	v_mfma_f32_32x32x16_bf16 v[16:31], v[140:143], v[152:155], v[16:31]
	v_mfma_f32_32x32x16_bf16 v[0:15], v[140:143], v[156:159], v[0:15]
	s_add_i32 s29, s29, -1
	s_cmp_lg_u32 s29, 0
	s_cbranch_scc0 .Lop4_exit
	s_waitcnt vmcnt(6)
	s_waitcnt lgkmcnt(0)
	s_barrier
	ds_read_b128 v[136:139], v222
	ds_read_b128 v[140:143], v222 offset:2048
	ds_read_b128 v[144:147], v223 offset:8192
	ds_read_b128 v[148:151], v223 offset:10240
	ds_read_b128 v[152:155], v223 offset:12288
	ds_read_b128 v[156:159], v223 offset:14336
	s_add_i32 s101, s100, 0x6000
	s_mov_b32 m0, s101
	v_mfma_f32_32x32x16_bf16 v[112:127], v[160:163], v[164:167], v[112:127]
	global_load_lds_dwordx4 v170, s[4:5]
	s_add_u32 m0, s101, 0x1000
	v_mfma_f32_32x32x16_bf16 v[96:111], v[160:163], v[180:183], v[96:111]
	global_load_lds_dwordx4 v171, s[4:5]
	s_add_u32 m0, s101, 0x2000
	v_mfma_f32_32x32x16_bf16 v[48:63], v[160:163], v[184:187], v[48:63]
	global_load_lds_dwordx4 v172, s[6:7]
	s_add_u32 m0, s101, 0x3000
	v_mfma_f32_32x32x16_bf16 v[32:47], v[160:163], v[188:191], v[32:47]
	global_load_lds_dwordx4 v170, s[6:7]
	s_add_u32 m0, s101, 0x4000
	v_mfma_f32_32x32x16_bf16 v[80:95], v[176:179], v[164:167], v[80:95]
	global_load_lds_dwordx4 v173, s[6:7]
	s_add_u32 m0, s101, 0x5000
	v_mfma_f32_32x32x16_bf16 v[64:79], v[176:179], v[180:183], v[64:79]
	global_load_lds_dwordx4 v171, s[6:7]
	s_add_u32 s4, s4, 0x10000
	s_addc_u32 s5, s5, 0
	s_add_u32 s6, s6, 0x120000
	s_addc_u32 s7, s7, 0
	v_mfma_f32_32x32x16_bf16 v[16:31], v[176:179], v[184:187], v[16:31]
	v_mfma_f32_32x32x16_bf16 v[0:15], v[176:179], v[188:191], v[0:15]
	s_waitcnt lgkmcnt(0)
	v_mfma_f32_32x32x16_bf16 v[112:127], v[136:139], v[144:147], v[112:127]
	ds_read_b128 v[160:163], v224
	v_mfma_f32_32x32x16_bf16 v[96:111], v[136:139], v[148:151], v[96:111]
	ds_read_b128 v[176:179], v224 offset:2048
	v_mfma_f32_32x32x16_bf16 v[48:63], v[136:139], v[152:155], v[48:63]
	ds_read_b128 v[164:167], v225 offset:8192
	v_mfma_f32_32x32x16_bf16 v[32:47], v[136:139], v[156:159], v[32:47]
	ds_read_b128 v[180:183], v225 offset:10240
	v_mfma_f32_32x32x16_bf16 v[80:95], v[140:143], v[144:147], v[80:95]
	ds_read_b128 v[184:187], v225 offset:12288
	v_mfma_f32_32x32x16_bf16 v[64:79], v[140:143], v[148:151], v[64:79]
	ds_read_b128 v[188:191], v225 offset:14336
	v_mfma_f32_32x32x16_bf16 v[16:31], v[140:143], v[152:155], v[16:31]
	v_mfma_f32_32x32x16_bf16 v[0:15], v[140:143], v[156:159], v[0:15]
	s_add_i32 s29, s29, -1
	s_cmp_lg_u32 s29, 0
	s_cbranch_scc0 .Lop4_exit
; #define MFMA(a, b, c) __builtin_amdgcn_mfma_f32_32x32x16_bf16((a), (b), (c), 0, 0, 0)
; #define G_ISSUE(ks_, buf_) do { \
;     const bf16_t* wq_ = wp + (ks_) * wks; const bf16_t* xq_ = xp + (ks_) * xks; char* lb_ = ld + (buf_) * STAGE; \
;     dma16(wq_, lb_); dma16(wq_ + 2048, lb_ + 4096); \
;     _Pragma("unroll") for (int i_ = 0; i_ < TJ; ++i_) dma16(xq_ + i_ * 2048, lb_ + 8192 + i_ * 4096); } while (0)
; template <bool VMODE, int TJ>
; DI void gemm_mainloop(const bf16_t* __restrict__ W, const bf16_t* __restrict__ X, int NW, char* smem, f32x16 (&acc)[2][TJ]) {
;     ...
;         for (int ks = 0; ks < 32; ++ks) {
;             if (ks < 31) asm volatile("s_waitcnt vmcnt(6)" ::: "memory");
;             else asm volatile("s_waitcnt vmcnt(0)" ::: "memory");
;             __builtin_amdgcn_s_barrier();
;             const char* sw = smem + bc * STAGE + wf * 64 * 64;
;             const char* sx = smem + bc * STAGE + 8192 + wt * (32 * TJ) * 64;
;             bf16x8 fw[2], fx[TJ], gw[2], gx[TJ];
; #pragma unroll
;             for (int i = 0; i < 2; ++i) fw[i] = *(const bf16x8*)(sw + i * 32 * 64 + fo0);
; #pragma unroll
;             for (int j = 0; j < TJ; ++j) fx[j] = *(const bf16x8*)(sx + j * 32 * 64 + fo0);
;             __builtin_amdgcn_sched_barrier(0);
;             if (ks + 2 < 32) G_ISSUE(ks + 2, bn);
;             __builtin_amdgcn_sched_barrier(0);
; #pragma unroll
;             for (int i = 0; i < 2; ++i) gw[i] = *(const bf16x8*)(sw + i * 32 * 64 + fo1);
; #pragma unroll
;             for (int j = 0; j < TJ; ++j) gx[j] = *(const bf16x8*)(sx + j * 32 * 64 + fo1);
; #pragma unroll
;             for (int i = 0; i < 2; ++i)
; #pragma unroll
;                 for (int j = 0; j < TJ; ++j) acc[i][j] = VMODE ? MFMA(fx[j], fw[i], acc[i][j]) : MFMA(fw[i], fx[j], acc[i][j]);
; #pragma unroll
;             for (int i = 0; i < 2; ++i)
; #pragma unroll
;                 for (int j = 0; j < TJ; ++j) acc[i][j] = VMODE ? MFMA(gx[j], gw[i], acc[i][j]) : MFMA(gw[i], gx[j], acc[i][j]);
	s_waitcnt vmcnt(6)
	s_waitcnt lgkmcnt(0)
	s_barrier
	ds_read_b128 v[136:139], v214
	ds_read_b128 v[140:143], v214 offset:2048
	ds_read_b128 v[144:147], v215 offset:8192
	ds_read_b128 v[148:151], v215 offset:10240
	ds_read_b128 v[152:155], v215 offset:12288
	ds_read_b128 v[156:159], v215 offset:14336
	s_add_i32 s101, s100, 0xc000
	s_mov_b32 m0, s101
	v_mfma_f32_32x32x16_bf16 v[112:127], v[160:163], v[164:167], v[112:127]
	global_load_lds_dwordx4 v170, s[4:5]
	s_add_u32 m0, s101, 0x1000
	v_mfma_f32_32x32x16_bf16 v[96:111], v[160:163], v[180:183], v[96:111]
	global_load_lds_dwordx4 v171, s[4:5]
	s_add_u32 m0, s101, 0x2000
	v_mfma_f32_32x32x16_bf16 v[48:63], v[160:163], v[184:187], v[48:63]
	global_load_lds_dwordx4 v172, s[6:7]
	s_add_u32 m0, s101, 0x3000
	v_mfma_f32_32x32x16_bf16 v[32:47], v[160:163], v[188:191], v[32:47]
	global_load_lds_dwordx4 v170, s[6:7]
	s_add_u32 m0, s101, 0x4000
	v_mfma_f32_32x32x16_bf16 v[80:95], v[176:179], v[164:167], v[80:95]
	global_load_lds_dwordx4 v173, s[6:7]
	s_add_u32 m0, s101, 0x5000
	v_mfma_f32_32x32x16_bf16 v[64:79], v[176:179], v[180:183], v[64:79]
	global_load_lds_dwordx4 v171, s[6:7]
	s_add_u32 s4, s4, 0x10000
	s_addc_u32 s5, s5, 0
	s_add_u32 s6, s6, 0x120000
	s_addc_u32 s7, s7, 0
	v_mfma_f32_32x32x16_bf16 v[16:31], v[176:179], v[184:187], v[16:31]
	v_mfma_f32_32x32x16_bf16 v[0:15], v[176:179], v[188:191], v[0:15]
	s_waitcnt lgkmcnt(0)
	v_mfma_f32_32x32x16_bf16 v[112:127], v[136:139], v[144:147], v[112:127]
	ds_read_b128 v[160:163], v216
	v_mfma_f32_32x32x16_bf16 v[96:111], v[136:139], v[148:151], v[96:111]
	ds_read_b128 v[176:179], v216 offset:2048
	v_mfma_f32_32x32x16_bf16 v[48:63], v[136:139], v[152:155], v[48:63]
	ds_read_b128 v[164:167], v217 offset:8192
	v_mfma_f32_32x32x16_bf16 v[32:47], v[136:139], v[156:159], v[32:47]
	ds_read_b128 v[180:183], v217 offset:10240
	v_mfma_f32_32x32x16_bf16 v[80:95], v[140:143], v[144:147], v[80:95]
	ds_read_b128 v[184:187], v217 offset:12288
	v_mfma_f32_32x32x16_bf16 v[64:79], v[140:143], v[148:151], v[64:79]
	ds_read_b128 v[188:191], v217 offset:14336
	v_mfma_f32_32x32x16_bf16 v[16:31], v[140:143], v[152:155], v[16:31]
	v_mfma_f32_32x32x16_bf16 v[0:15], v[140:143], v[156:159], v[0:15]
	s_add_i32 s29, s29, -1
	s_cmp_lg_u32 s29, 0
	s_cbranch_scc1 .Lop4_loop
; #define MFMA(a, b, c) __builtin_amdgcn_mfma_f32_32x32x16_bf16((a), (b), (c), 0, 0, 0)
; template <bool VMODE, int TJ>
; DI void gemm_mainloop(const bf16_t* __restrict__ W, const bf16_t* __restrict__ X, int NW, char* smem, f32x16 (&acc)[2][TJ]) {
;     ...
;         for (int ks = 0; ks < 32; ++ks) {
;             if (ks < 31) asm volatile("s_waitcnt vmcnt(6)" ::: "memory");
;             else asm volatile("s_waitcnt vmcnt(0)" ::: "memory");
;             __builtin_amdgcn_s_barrier();
;             const char* sw = smem + bc * STAGE + wf * 64 * 64;
;             const char* sx = smem + bc * STAGE + 8192 + wt * (32 * TJ) * 64;
;             bf16x8 fw[2], fx[TJ], gw[2], gx[TJ];
; #pragma unroll
;             for (int i = 0; i < 2; ++i) fw[i] = *(const bf16x8*)(sw + i * 32 * 64 + fo0);
; #pragma unroll
;             for (int j = 0; j < TJ; ++j) fx[j] = *(const bf16x8*)(sx + j * 32 * 64 + fo0);
;             __builtin_amdgcn_sched_barrier(0);
;             if (ks + 2 < 32) G_ISSUE(ks + 2, bn);
;             __builtin_amdgcn_sched_barrier(0);
; #pragma unroll
;             for (int i = 0; i < 2; ++i) gw[i] = *(const bf16x8*)(sw + i * 32 * 64 + fo1);
; #pragma unroll
;             for (int j = 0; j < TJ; ++j) gx[j] = *(const bf16x8*)(sx + j * 32 * 64 + fo1);
; #pragma unroll
;             for (int i = 0; i < 2; ++i)
; #pragma unroll
;                 for (int j = 0; j < TJ; ++j) acc[i][j] = VMODE ? MFMA(fx[j], fw[i], acc[i][j]) : MFMA(fw[i], fx[j], acc[i][j]);
; #pragma unroll
;             for (int i = 0; i < 2; ++i)
; #pragma unroll
;                 for (int j = 0; j < TJ; ++j) acc[i][j] = VMODE ? MFMA(gx[j], gw[i], acc[i][j]) : MFMA(gw[i], gx[j], acc[i][j]);
;             bc = (bc == 2) ? 0 : bc + 1; bn = (bn == 2) ? 0 : bn + 1;
;         }
;     }
;     ...
;     __syncthreads();
; template <int TJ>
; DI void outproj_tile(const Params& p, int l, char* smem, int b, int trow0, int n0) {
;     ...
;     const float* gt = p.mod + ((size_t)l * 9 + (trow0 < SEQ ? b : 8)) * 3072 + 2048 + n0 + 64 * wf;
;     const float* xs = src_row(p, l, b, trow0 + 32 * TJ * wt) + n0 + 64 * wf;
;     float* xd = dst_row(p, b, trow0 + 32 * TJ * wt) + n0 + 64 * wf;
.Lop4_exit:
	s_waitcnt vmcnt(6)
	s_waitcnt lgkmcnt(0)
	s_barrier
	ds_read_b128 v[136:139], v214
	ds_read_b128 v[140:143], v214 offset:2048
	ds_read_b128 v[144:147], v215 offset:8192
	ds_read_b128 v[148:151], v215 offset:10240
	ds_read_b128 v[152:155], v215 offset:12288
	ds_read_b128 v[156:159], v215 offset:14336
	v_mfma_f32_32x32x16_bf16 v[112:127], v[160:163], v[164:167], v[112:127]
	v_mfma_f32_32x32x16_bf16 v[96:111], v[160:163], v[180:183], v[96:111]
	v_mfma_f32_32x32x16_bf16 v[48:63], v[160:163], v[184:187], v[48:63]
	v_mfma_f32_32x32x16_bf16 v[32:47], v[160:163], v[188:191], v[32:47]
	v_mfma_f32_32x32x16_bf16 v[80:95], v[176:179], v[164:167], v[80:95]
	v_mfma_f32_32x32x16_bf16 v[64:79], v[176:179], v[180:183], v[64:79]
	v_mfma_f32_32x32x16_bf16 v[16:31], v[176:179], v[184:187], v[16:31]
	v_mfma_f32_32x32x16_bf16 v[0:15], v[176:179], v[188:191], v[0:15]
	s_waitcnt lgkmcnt(0)
	v_mfma_f32_32x32x16_bf16 v[112:127], v[136:139], v[144:147], v[112:127]
	ds_read_b128 v[160:163], v216
	v_mfma_f32_32x32x16_bf16 v[96:111], v[136:139], v[148:151], v[96:111]
	ds_read_b128 v[176:179], v216 offset:2048
	v_mfma_f32_32x32x16_bf16 v[48:63], v[136:139], v[152:155], v[48:63]
	ds_read_b128 v[164:167], v217 offset:8192
	v_mfma_f32_32x32x16_bf16 v[32:47], v[136:139], v[156:159], v[32:47]
	ds_read_b128 v[180:183], v217 offset:10240
	v_mfma_f32_32x32x16_bf16 v[80:95], v[140:143], v[144:147], v[80:95]
	ds_read_b128 v[184:187], v217 offset:12288
	v_mfma_f32_32x32x16_bf16 v[64:79], v[140:143], v[148:151], v[64:79]
	ds_read_b128 v[188:191], v217 offset:14336
	v_mfma_f32_32x32x16_bf16 v[16:31], v[140:143], v[152:155], v[16:31]
	v_mfma_f32_32x32x16_bf16 v[0:15], v[140:143], v[156:159], v[0:15]
	s_waitcnt vmcnt(0)
	s_waitcnt lgkmcnt(0)
	s_barrier
	ds_read_b128 v[136:139], v218
	ds_read_b128 v[140:143], v218 offset:2048
	ds_read_b128 v[144:147], v219 offset:8192
	ds_read_b128 v[148:151], v219 offset:10240
	ds_read_b128 v[152:155], v219 offset:12288
	ds_read_b128 v[156:159], v219 offset:14336
	v_mfma_f32_32x32x16_bf16 v[112:127], v[160:163], v[164:167], v[112:127]
	v_mfma_f32_32x32x16_bf16 v[96:111], v[160:163], v[180:183], v[96:111]
	v_mfma_f32_32x32x16_bf16 v[48:63], v[160:163], v[184:187], v[48:63]
	v_mfma_f32_32x32x16_bf16 v[32:47], v[160:163], v[188:191], v[32:47]
	v_mfma_f32_32x32x16_bf16 v[80:95], v[176:179], v[164:167], v[80:95]
	v_mfma_f32_32x32x16_bf16 v[64:79], v[176:179], v[180:183], v[64:79]
	v_mfma_f32_32x32x16_bf16 v[16:31], v[176:179], v[184:187], v[16:31]
	v_mfma_f32_32x32x16_bf16 v[0:15], v[176:179], v[188:191], v[0:15]
	s_waitcnt lgkmcnt(0)
	v_mfma_f32_32x32x16_bf16 v[112:127], v[136:139], v[144:147], v[112:127]
	ds_read_b128 v[160:163], v220
	v_mfma_f32_32x32x16_bf16 v[96:111], v[136:139], v[148:151], v[96:111]
	ds_read_b128 v[176:179], v220 offset:2048
	v_mfma_f32_32x32x16_bf16 v[48:63], v[136:139], v[152:155], v[48:63]
	ds_read_b128 v[164:167], v221 offset:8192
	v_mfma_f32_32x32x16_bf16 v[32:47], v[136:139], v[156:159], v[32:47]
	ds_read_b128 v[180:183], v221 offset:10240
	v_mfma_f32_32x32x16_bf16 v[80:95], v[140:143], v[144:147], v[80:95]
	ds_read_b128 v[184:187], v221 offset:12288
	v_mfma_f32_32x32x16_bf16 v[64:79], v[140:143], v[148:151], v[64:79]
	ds_read_b128 v[188:191], v221 offset:14336
	v_mfma_f32_32x32x16_bf16 v[16:31], v[140:143], v[152:155], v[16:31]
	v_mfma_f32_32x32x16_bf16 v[0:15], v[140:143], v[156:159], v[0:15]
	s_waitcnt lgkmcnt(0)
	v_mfma_f32_32x32x16_bf16 v[112:127], v[160:163], v[164:167], v[112:127]
	v_mfma_f32_32x32x16_bf16 v[96:111], v[160:163], v[180:183], v[96:111]
	v_mfma_f32_32x32x16_bf16 v[48:63], v[160:163], v[184:187], v[48:63]
	v_mfma_f32_32x32x16_bf16 v[32:47], v[160:163], v[188:191], v[32:47]
	v_mfma_f32_32x32x16_bf16 v[80:95], v[176:179], v[164:167], v[80:95]
	v_mfma_f32_32x32x16_bf16 v[64:79], v[176:179], v[180:183], v[64:79]
	v_mfma_f32_32x32x16_bf16 v[16:31], v[176:179], v[184:187], v[16:31]
	v_mfma_f32_32x32x16_bf16 v[0:15], v[176:179], v[188:191], v[0:15]
	s_waitcnt vmcnt(0) lgkmcnt(0)
	s_barrier
	s_nop 7
	s_nop 7
	v_mov_b32_e32 v172, v64
	v_mov_b32_e32 v173, v65
	v_mov_b32_e32 v174, v66
	v_mov_b32_e32 v175, v67
	v_mov_b32_e32 v176, v68
	v_mov_b32_e32 v177, v69
	v_mov_b32_e32 v178, v70
	v_mov_b32_e32 v179, v71
	v_mov_b32_e32 v180, v72
	v_mov_b32_e32 v181, v73
	v_mov_b32_e32 v182, v74
	v_mov_b32_e32 v183, v75
	v_mov_b32_e32 v184, v76
	v_mov_b32_e32 v185, v77
	v_mov_b32_e32 v186, v78
	v_mov_b32_e32 v187, v79
	v_mov_b32_e32 v188, v80
	v_mov_b32_e32 v189, v81
	v_mov_b32_e32 v190, v82
	v_mov_b32_e32 v191, v83
	v_mov_b32_e32 v194, v84
	v_mov_b32_e32 v195, v85
	v_mov_b32_e32 v196, v86
	v_mov_b32_e32 v197, v87
	v_mov_b32_e32 v198, v88
	v_mov_b32_e32 v199, v89
	v_mov_b32_e32 v214, v90
	v_mov_b32_e32 v215, v91
	v_mov_b32_e32 v216, v92
	v_mov_b32_e32 v217, v93
	v_mov_b32_e32 v218, v94
	v_mov_b32_e32 v219, v95
	v_mov_b32_e32 v220, v96
	v_mov_b32_e32 v221, v97
	v_mov_b32_e32 v222, v98
	v_mov_b32_e32 v223, v99
	v_mov_b32_e32 v224, v100
	v_mov_b32_e32 v225, v101
	v_mov_b32_e32 v226, v102
	v_mov_b32_e32 v227, v103
	v_mov_b32_e32 v228, v104
	v_mov_b32_e32 v229, v105
	v_mov_b32_e32 v230, v106
	v_mov_b32_e32 v231, v107
	v_mov_b32_e32 v232, v108
	v_mov_b32_e32 v233, v109
	v_mov_b32_e32 v234, v110
	v_mov_b32_e32 v235, v111
	v_mov_b32_e32 v236, v112
	v_mov_b32_e32 v237, v113
	v_mov_b32_e32 v238, v114
	v_mov_b32_e32 v239, v115
	v_mov_b32_e32 v240, v116
	v_mov_b32_e32 v241, v117
	v_mov_b32_e32 v242, v118
	v_mov_b32_e32 v243, v119
	v_mov_b32_e32 v244, v120
	v_mov_b32_e32 v245, v121
	v_mov_b32_e32 v246, v122
	v_mov_b32_e32 v247, v123
	v_mov_b32_e32 v248, v124
	v_mov_b32_e32 v249, v125
	v_mov_b32_e32 v250, v126
	v_mov_b32_e32 v251, v127
	v_mov_b32_e32 v116, v200
	s_mov_b64 s[4:5], -1
	s_and_b64 vcc, exec, s[50:51]
	s_load_dwordx2 s[52:53], s[0:1], 0xe0
	v_ashrrev_i32_e32 v64, 1, v116
	v_and_b32_e32 v64, 0xffffffc0, v64
	v_add_u32_e32 v66, s28, v64
	v_cmp_gt_i32_e64 s[40:41], s61, v66
	v_cmp_lt_i32_e64 s[42:43], s21, v66
	s_branch .Lop4_epi
